# attention loop edge: K/V fragment LDS reads issued right after barrier release, tile global loads and their SALU setup moved behind them
# speedup vs baseline: 1.0131x; 1.0075x over previous
; __device__ __forceinline__ float max3f(float a, float b, float c) { float d; asm("v_max3_f32 %0, %1, %2, %3" : "=v"(d) : "v"(a), "v"(b), "v"(c)); return d; }
; #define ATT_LOADK(rk, rr, kt_) do { if (MODE == 3 && (kt_) > 1) break; rk = *(const u32x4*)(gkn + (size_t)(kt_) * 64 * 512); rr = *(const u32x4*)(gkr + (size_t)(kt_) * 64 * 32); } while (0)
; #define ATT_LOADV(rv, kt_) do { if (MODE == 3 && (kt_) > 1) break; rv = *(const u32x4*)(gvt + (size_t)(kt_) * 64); } while (0)
; #define ATT_WRITEK(rk, rr, buf) do { LAS unsigned char* nb_ = lds + (buf) * KBUF; *(LAS u32x4*)(nb_ + skn) = rk; if (tid < 256) *(LAS u32x4*)(nb_ + skr) = rr; } while (0)
; template <int MODE>
; __device__ __forceinline__ void attn_pv(const LAS unsigned char* vb_, f32x16 (&st)[2], f32x16 (&ot)[2], float& mrun, float& lsum, const int ql, const int hf, const int lane) {
;     if (MODE != 1) {
;     float mx = max3f(st[0][0], st[1][0], st[0][1]), my = max3f(st[1][1], st[0][2], st[1][2]);
; #pragma unroll
;     for (int i = 3; i < 15; i += 2) { mx = max3f(mx, st[0][i], st[1][i]); my = max3f(my, st[0][i + 1], st[1][i + 1]); }
;     mx = max3f(mx, st[0][15], st[1][15]); mx = max3f(mx, my, my);
;     if (__builtin_amdgcn_ballot_w64(mx > mrun + 8.0f) != 0ull) {
; template <int MODE>
; __device__ __forceinline__ void attn_phase(const Args& a, bool do_ctx, LAS unsigned char* lds, const int wid_s) {
;     ...
;         for (int t = 0; t < nkt; t += 2) {
;             if (t + 2 < nkt) ATT_LOADK(kK, kR, t + 2);
;             ATT_LOADV(vV, t + 1);
;             attn_qk<MODE>(lds + KBUF, qf, sb, ql, hf);
;             __builtin_amdgcn_sched_barrier(0);
;             attn_pv<MODE>(ldsv, sa, ot, mrun, lsum, ql, hf, lane);
;             if (t + 2 < nkt) ATT_WRITEK(kK, kR, 0);
.LBB0_435:
	s_add_i32 s13, s12, -1
	s_cmp_lt_u32 s13, s25
	s_cselect_b64 s[10:11], -1, 0
	s_cmp_lg_u32 s96, 0
	s_cbranch_scc1 .LattB_e
	ds_read_b128 v[64:67], v165 offset:13312
	ds_read_b128 v[168:171], v165 offset:13344
	ds_read_b128 v[68:71], v165 offset:19968
	ds_read_b128 v[172:175], v165 offset:20000
	ds_read_b128 v[176:179], v165 offset:13376
	ds_read_b128 v[180:183], v165 offset:13408
	ds_read_b128 v[184:187], v165 offset:20032
	ds_read_b128 v[188:191], v165 offset:20064
	ds_read_b128 v[206:209], v240 offset:31232
	ds_read_b128 v[210:213], v240 offset:26624
	ds_read_b128 v[214:217], v240 offset:31264
	ds_read_b128 v[218:221], v240 offset:26656
	ds_read_b128 v[222:225], v240 offset:31296
	ds_read_b128 v[226:229], v240 offset:26688
	ds_read_b128 v[236:239], v240 offset:26720
	s_andn2_b64 vcc, exec, s[10:11]
	s_cbranch_vccnz .Latt_eA_noK
	global_load_dwordx4 v[120:123], v146, s[80:81]
	global_load_dwordx4 v[124:127], v148, s[82:83]
.Latt_eA_noK:
	global_load_dwordx4 v[128:131], v150, s[84:85] offset:128
	v_max3_f32 v156, v48, v32, v49
	v_max3_f32 v157, v33, v50, v34
	v_max3_f32 v156, v156, v51, v35
	v_max3_f32 v157, v157, v52, v36
	v_max3_f32 v156, v156, v53, v37
	v_max3_f32 v157, v157, v54, v38
	v_max3_f32 v156, v156, v55, v39
	v_max3_f32 v157, v157, v56, v40
	v_max3_f32 v156, v156, v57, v41
	v_max3_f32 v157, v157, v58, v42
	v_max3_f32 v156, v156, v59, v43
	v_max3_f32 v157, v157, v60, v44
	v_max3_f32 v156, v156, v61, v45
	v_max3_f32 v157, v157, v62, v46
	v_max3_f32 v156, v156, v63, v47
	v_max3_f32 v157, v156, v157, v157
	v_add_f32_e32 v156, 0x41000000, v143
	v_cmp_gt_f32_e32 vcc, v157, v156
	s_cbranch_vccnz .Latt_e_nors_resc

; __device__ __forceinline__ float max3f(float a, float b, float c) { float d; asm("v_max3_f32 %0, %1, %2, %3" : "=v"(d) : "v"(a), "v"(b), "v"(c)); return d; }
; #define ATT_LOADK(rk, rr, kt_) do { if (MODE == 3 && (kt_) > 1) break; rk = *(const u32x4*)(gkn + (size_t)(kt_) * 64 * 512); rr = *(const u32x4*)(gkr + (size_t)(kt_) * 64 * 32); } while (0)
; #define ATT_LOADV(rv, kt_) do { if (MODE == 3 && (kt_) > 1) break; rv = *(const u32x4*)(gvt + (size_t)(kt_) * 64); } while (0)
; template <int MODE>
; __device__ __forceinline__ void attn_pv(const LAS unsigned char* vb_, f32x16 (&st)[2], f32x16 (&ot)[2], float& mrun, float& lsum, const int ql, const int hf, const int lane) {
;     if (MODE != 1) {
;     float mx = max3f(st[0][0], st[1][0], st[0][1]), my = max3f(st[1][1], st[0][2], st[1][2]);
; #pragma unroll
;     for (int i = 3; i < 15; i += 2) { mx = max3f(mx, st[0][i], st[1][i]); my = max3f(my, st[0][i + 1], st[1][i + 1]); }
;     mx = max3f(mx, st[0][15], st[1][15]); mx = max3f(mx, my, my);
;     if (__builtin_amdgcn_ballot_w64(mx > mrun + 8.0f) != 0ull) {
; template <int MODE>
; __device__ __forceinline__ void attn_phase(const Args& a, bool do_ctx, LAS unsigned char* lds, const int wid_s) {
;     ...
;             if (t + 3 < nkt) ATT_LOADK(kK, kR, t + 3);
;             if (t + 2 < nkt) ATT_LOADV(vV, t + 2);
;             if (t + 2 < nkt) attn_qk<MODE>(lds, qf, sa, ql, hf);
;             __builtin_amdgcn_sched_barrier(0);
;             attn_pv<MODE>(ldsv + VBUF, sb, ot, mrun, lsum, ql, hf, lane);
.Latt_otop:
	s_and_b64 vcc, exec, s[8:9]
	s_cbranch_vccnz .Latt_o_tail
	s_cmp_lg_u32 s96, 0
	s_cbranch_scc1 .LattB_o
	ds_read_b128 v[32:35], v165
	ds_read_b128 v[152:155], v165 offset:32
	ds_read_b128 v[36:39], v165 offset:6656
	ds_read_b128 v[206:209], v165 offset:6688
	ds_read_b128 v[210:213], v165 offset:64
	ds_read_b128 v[214:217], v165 offset:96
	ds_read_b128 v[218:221], v165 offset:6720
	ds_read_b128 v[222:225], v165 offset:6752
	ds_read_b128 v[176:179], v240 offset:35840
	ds_read_b128 v[180:183], v240 offset:40448
	ds_read_b128 v[184:187], v240 offset:35872
	ds_read_b128 v[188:191], v240 offset:40480
	ds_read_b128 v[192:195], v240 offset:35904
	ds_read_b128 v[196:199], v240 offset:40512
	ds_read_b128 v[172:175], v240 offset:35936
	s_andn2_b64 vcc, exec, s[10:11]
	s_cbranch_vccnz .Latt_oA_noK
	s_add_u32 s86, s80, 0x10000
	s_addc_u32 s87, s81, 0
	s_add_u32 s88, s82, 0x1000
	s_addc_u32 s89, s83, 0
	global_load_dwordx4 v[120:123], v146, s[86:87]
	global_load_dwordx4 v[124:127], v148, s[88:89]
.Latt_oA_noK:
	global_load_dwordx4 v[128:131], v150, s[84:85] offset:256
	v_max3_f32 v156, v80, v64, v81
	v_max3_f32 v157, v65, v82, v66
	v_max3_f32 v156, v156, v83, v67
	v_max3_f32 v157, v157, v84, v68
	v_max3_f32 v156, v156, v85, v69
	v_max3_f32 v157, v157, v86, v70
	v_max3_f32 v156, v156, v87, v71
	v_max3_f32 v157, v157, v88, v72
	v_max3_f32 v156, v156, v89, v73
	v_max3_f32 v157, v157, v90, v74
	v_max3_f32 v156, v156, v91, v75
	v_max3_f32 v157, v157, v92, v76
	v_max3_f32 v156, v156, v93, v77
	v_max3_f32 v157, v157, v94, v78
	v_max3_f32 v156, v156, v95, v79
	v_max3_f32 v157, v156, v157, v157
	v_add_f32_e32 v156, 0x41000000, v143
	v_cmp_gt_f32_e32 vcc, v157, v156
	s_cbranch_vccnz .Latt_o_nors_resc

; #define ATT_LOADK(rk, rr, kt_) do { if (MODE == 3 && (kt_) > 1) break; rk = *(const u32x4*)(gkn + (size_t)(kt_) * 64 * 512); rr = *(const u32x4*)(gkr + (size_t)(kt_) * 64 * 32); } while (0)
; #define ATT_LOADV(rv, kt_) do { if (MODE == 3 && (kt_) > 1) break; rv = *(const u32x4*)(gvt + (size_t)(kt_) * 64); } while (0)
; template <int MODE>
; __device__ __forceinline__ void attn_phase(const Args& a, bool do_ctx, LAS unsigned char* lds, const int wid_s) {
;     ...
;             if (t + 2 < nkt) ATT_LOADK(kK, kR, t + 2);
;             ATT_LOADV(vV, t + 1);
.LattB_e:
	s_andn2_b64 vcc, exec, s[10:11]
	s_cbranch_vccnz .Latt_eB_noK
	global_load_dwordx4 v[120:123], v146, s[80:81]
	global_load_dwordx4 v[124:127], v148, s[82:83]

; __device__ __forceinline__ float max3f(float a, float b, float c) { float d; asm("v_max3_f32 %0, %1, %2, %3" : "=v"(d) : "v"(a), "v"(b), "v"(c)); return d; }
; #define ATT_LOADK(rk, rr, kt_) do { if (MODE == 3 && (kt_) > 1) break; rk = *(const u32x4*)(gkn + (size_t)(kt_) * 64 * 512); rr = *(const u32x4*)(gkr + (size_t)(kt_) * 64 * 32); } while (0)
; #define ATT_LOADV(rv, kt_) do { if (MODE == 3 && (kt_) > 1) break; rv = *(const u32x4*)(gvt + (size_t)(kt_) * 64); } while (0)
; template <int MODE>
; __device__ __forceinline__ void attn_pv(const LAS unsigned char* vb_, f32x16 (&st)[2], f32x16 (&ot)[2], float& mrun, float& lsum, const int ql, const int hf, const int lane) {
;     if (MODE != 1) {
;     float mx = max3f(st[0][0], st[1][0], st[0][1]), my = max3f(st[1][1], st[0][2], st[1][2]);
; #pragma unroll
;     for (int i = 3; i < 15; i += 2) { mx = max3f(mx, st[0][i], st[1][i]); my = max3f(my, st[0][i + 1], st[1][i + 1]); }
;     mx = max3f(mx, st[0][15], st[1][15]); mx = max3f(mx, my, my);
;     if (__builtin_amdgcn_ballot_w64(mx > mrun + 8.0f) != 0ull) {
; template <int MODE>
; __device__ __forceinline__ void attn_phase(const Args& a, bool do_ctx, LAS unsigned char* lds, const int wid_s) {
;     ...
;             if (t + 3 < nkt) ATT_LOADK(kK, kR, t + 3);
;             if (t + 2 < nkt) ATT_LOADV(vV, t + 2);
;             if (t + 2 < nkt) attn_qk<MODE>(lds, qf, sa, ql, hf);
;             __builtin_amdgcn_sched_barrier(0);
;             attn_pv<MODE>(ldsv + VBUF, sb, ot, mrun, lsum, ql, hf, lane);
.LattB_o:
	s_andn2_b64 vcc, exec, s[10:11]
	s_cbranch_vccnz .Latt_oB_noK
	s_add_u32 s86, s80, 0x10000
	s_addc_u32 s87, s81, 0
	s_add_u32 s88, s82, 0x1000
	s_addc_u32 s89, s83, 0
	global_load_dwordx4 v[120:123], v146, s[86:87]
	global_load_dwordx4 v[124:127], v148, s[88:89]
.Latt_oB_noK:
	global_load_dwordx4 v[128:131], v150, s[84:85] offset:256
	ds_read_b128 v[32:35], v165
	ds_read_b128 v[152:155], v165 offset:32
	ds_read_b128 v[36:39], v165 offset:6656
	ds_read_b128 v[206:209], v165 offset:6688
	ds_read_b128 v[210:213], v165 offset:64
	ds_read_b128 v[214:217], v165 offset:96
	ds_read_b128 v[218:221], v165 offset:6720
	ds_read_b128 v[222:225], v165 offset:6752
	ds_read_b128 v[176:179], v240 offset:35840
	ds_read_b128 v[180:183], v240 offset:40448
	ds_read_b128 v[184:187], v240 offset:35872
	ds_read_b128 v[188:191], v240 offset:40480
	ds_read_b128 v[192:195], v240 offset:35904
	ds_read_b128 v[196:199], v240 offset:40512
	ds_read_b128 v[172:175], v240 offset:35936
	v_max3_f32 v156, v80, v64, v81
	v_max3_f32 v157, v65, v82, v66
	v_max3_f32 v156, v156, v83, v67
	v_max3_f32 v157, v157, v84, v68
	v_max3_f32 v156, v156, v85, v69
	v_max3_f32 v157, v157, v86, v70
	v_max3_f32 v156, v156, v87, v71
	v_max3_f32 v157, v157, v88, v72
	v_max3_f32 v156, v156, v89, v73
	v_max3_f32 v157, v157, v90, v74
	v_max3_f32 v156, v156, v91, v75
	v_max3_f32 v157, v157, v92, v76
	v_max3_f32 v156, v156, v93, v77
	v_max3_f32 v157, v157, v94, v78
	v_max3_f32 v156, v156, v95, v79
	v_max3_f32 v157, v156, v157, v157
	v_add_f32_e32 v156, 0x41000000, v143
	v_cmp_gt_f32_e32 vcc, v157, v156
	s_cbranch_vccnz .Latt_oB_nors_resc
